# g1_epires_rebal_mlstm_dpp_scan
# speedup vs baseline: 1.0103x; 1.0103x over previous
; __device__ __forceinline__ void mlstm_item8(const Params& p, unsigned char* lds, int item) {
;     ...
;       float bb = lf;
; #pragma unroll
;       for (int o = 1; o < 64; o <<= 1) { const float t = __shfl_up(bb, o); if (lane >= o) bb += t; }
;       const float g = __shfl(bb, 63);
;       const float cs = li - bb;
;       float pm = cs;
; #pragma unroll
;       for (int o = 1; o < 64; o <<= 1) { const float t = __shfl_up(pm, o); if (lane >= o) pm = fmaxf(pm, t); }
;       const float pmax = __shfl(pm, 63);
;       const float inter = bb + m_state, mrow = fmaxf(inter, bb + pm);
;       rowt[lane] = bb - mrow; cols[lane] = cs; winter[lane] = __expf(inter - mrow); emr[lane] = __expf(-mrow);
;       const float m_new = fmaxf(g + m_state, g + pmax);
;       wkv[lane] = __expf(g + cs - m_new);
;       if (lane == 0) scal[0] = __expf(g + m_state - m_new);
;       m_state = m_new;
.LBB0_354:
	s_or_b64 exec, exec, s[44:45]
	v_cmp_lt_i32_e64 s[44:45], v73, v72
	s_waitcnt vmcnt(1)
	v_add_f32_e32 v44, v82, v84
	v_cndmask_b32_e32 v44, v80, v44, vcc
	v_mov_b32_e32 v38, v36
	s_nop 1
	v_add_f32_dpp v38, v38, v38 row_shr:1 row_mask:0xf bank_mask:0xf
	s_nop 1
	v_add_f32_dpp v38, v38, v38 row_shr:2 row_mask:0xf bank_mask:0xf
	s_nop 1
	v_add_f32_dpp v38, v38, v38 row_shr:4 row_mask:0xf bank_mask:0xf
	s_nop 1
	v_add_f32_dpp v38, v38, v38 row_shr:8 row_mask:0xf bank_mask:0xf
	s_nop 1
	v_add_f32_dpp v38, v38, v38 row_bcast:15 row_mask:0xa bank_mask:0xf
	s_nop 1
	v_add_f32_dpp v38, v38, v38 row_bcast:31 row_mask:0xc bank_mask:0xf
	v_sub_f32_e32 v44, v44, v38
	v_mov_b32_e32 v37, v44
	s_nop 1
	v_max_f32_dpp v37, v37, v37 row_shr:1 row_mask:0xf bank_mask:0xf
	s_nop 1
	v_max_f32_dpp v37, v37, v37 row_shr:2 row_mask:0xf bank_mask:0xf
	s_nop 1
	v_max_f32_dpp v37, v37, v37 row_shr:4 row_mask:0xf bank_mask:0xf
	s_nop 1
	v_max_f32_dpp v37, v37, v37 row_shr:8 row_mask:0xf bank_mask:0xf
	s_nop 1
	v_max_f32_dpp v37, v37, v37 row_bcast:15 row_mask:0xa bank_mask:0xf
	s_nop 1
	v_max_f32_dpp v37, v37, v37 row_bcast:31 row_mask:0xc bank_mask:0xf
	s_nop 0
	v_readlane_b32 s44, v38, 63
	v_readlane_b32 s45, v37, 63
	v_add_f32_e32 v41, v57, v38
	s_nop 0
	v_mov_b32_e32 v39, s44
	v_mov_b32_e32 v40, s45
	v_add_f32_e32 v36, v57, v39
	v_add_f32_e32 v37, v38, v37
	v_max_f32_e32 v37, v41, v37
	v_sub_f32_e32 v38, v38, v37
	v_sub_f32_e32 v41, v41, v37
	v_add_f32_e32 v40, v39, v40
	ds_write_b32 v86, v38
	v_mul_f32_e32 v38, 0x3fb8aa3b, v41
	v_max_f32_e32 v57, v36, v40
	v_add_f32_e32 v39, v44, v39
	v_mul_f32_e32 v37, 0xbfb8aa3b, v37
	v_exp_f32_e32 v38, v38
	v_sub_f32_e32 v39, v39, v57
	v_exp_f32_e32 v37, v37
	v_mul_f32_e32 v39, 0x3fb8aa3b, v39
	v_exp_f32_e32 v39, v39
	ds_write_b32 v87, v44
	ds_write_b32 v88, v38
	ds_write_b32 v89, v37
	ds_write_b32 v90, v39
	s_and_saveexec_b64 s[44:45], s[4:5]
	s_cbranch_execz .LBB0_356
	v_sub_f32_e32 v36, v36, v57
	v_mul_f32_e32 v36, 0x3fb8aa3b, v36
	v_exp_f32_e32 v36, v36
	ds_write_b32 v78, v36

;     __device__ __forceinline__ void operator()(const f32x4 (&acc)[2][2][4][2], const Unit& u, int wr, int wc, int fr, int fq) const {
;     ...
;             for (int m = 0; m < 4; ++m) { const int row = row0 + ai * HALF + m * 16;
;                 if (row < M) { float* hp = hrow(*p, row) + col0; const float* sp = FIRST ? xrow(*p, row) + col0 : hp;
; #pragma unroll
;                     for (int bj = 0; bj < 2; ++bj)
; #pragma unroll
;                         for (int n = 0; n < 2; ++n) { f32x4 h = *(const f32x4*)(sp + bj * HALF + n * 16); h += acc[ai][bj][m][n]; *(f32x4*)(hp + bj * HALF + n * 16) = h; } } }
.LBB0_874:
	s_andn2_saveexec_b64 s[18:19], s[18:19]
	v_ashrrev_i32_e32 v151, 31, v150
	s_or_b64 exec, exec, s[18:19]
	v_lshlrev_b64 v[152:153], 12, v[152:153]
	v_lshlrev_b64 v[150:151], 12, v[150:151]
	v_lshl_add_u64 v[152:153], v[154:155], 0, v[152:153]
	v_lshlrev_b64 v[154:155], 2, v[148:149]
	v_lshl_add_u64 v[150:151], v[158:159], 0, v[150:151]
	v_lshl_add_u64 v[156:157], v[152:153], 0, v[154:155]
	v_lshl_add_u64 v[154:155], v[150:151], 0, v[154:155]
	global_load_dwordx4 v[212:215], v[154:155], off
	global_load_dwordx4 v[216:219], v[154:155], off offset:64
	global_load_dwordx4 v[220:223], v[154:155], off offset:512
	global_load_dwordx4 v[224:227], v[154:155], off offset:576
	s_waitcnt vmcnt(3)
	v_pk_add_f32 v[126:127], v[126:127], v[214:215]
	v_pk_add_f32 v[124:125], v[124:125], v[212:213]
	global_store_dwordx4 v[156:157], v[124:127], off
	s_waitcnt vmcnt(3)
	v_pk_add_f32 v[122:123], v[122:123], v[218:219]
	v_pk_add_f32 v[120:121], v[120:121], v[216:217]
	global_store_dwordx4 v[156:157], v[120:123], off offset:64
	s_waitcnt vmcnt(3)
	v_pk_add_f32 v[118:119], v[118:119], v[222:223]
	v_pk_add_f32 v[116:117], v[116:117], v[220:221]
	global_store_dwordx4 v[156:157], v[116:119], off offset:512
	s_waitcnt vmcnt(3)
	v_pk_add_f32 v[114:115], v[114:115], v[226:227]
	v_pk_add_f32 v[112:113], v[112:113], v[224:225]
	global_store_dwordx4 v[156:157], v[112:115], off offset:576

;     __device__ __forceinline__ void operator()(const f32x4 (&acc)[2][2][4][2], const Unit& u, int wr, int wc, int fr, int fq) const {
;     ...
;             for (int m = 0; m < 4; ++m) { const int row = row0 + ai * HALF + m * 16;
;                 if (row < M) { float* hp = hrow(*p, row) + col0; const float* sp = FIRST ? xrow(*p, row) + col0 : hp;
; #pragma unroll
;                     for (int bj = 0; bj < 2; ++bj)
; #pragma unroll
;                         for (int n = 0; n < 2; ++n) { f32x4 h = *(const f32x4*)(sp + bj * HALF + n * 16); h += acc[ai][bj][m][n]; *(f32x4*)(hp + bj * HALF + n * 16) = h; } } }
.LBB0_884:
	s_andn2_saveexec_b64 s[18:19], s[18:19]
	v_ashrrev_i32_e32 v113, 31, v112
	s_or_b64 exec, exec, s[18:19]
	v_lshlrev_b64 v[114:115], 12, v[114:115]
	v_lshlrev_b64 v[112:113], 12, v[112:113]
	v_lshl_add_u64 v[114:115], v[116:117], 0, v[114:115]
	v_lshlrev_b64 v[116:117], 2, v[148:149]
	v_lshl_add_u64 v[112:113], v[120:121], 0, v[112:113]
	v_lshl_add_u64 v[118:119], v[114:115], 0, v[116:117]
	v_lshl_add_u64 v[116:117], v[112:113], 0, v[116:117]
	global_load_dwordx4 v[212:215], v[116:117], off
	global_load_dwordx4 v[216:219], v[116:117], off offset:64
	global_load_dwordx4 v[220:223], v[116:117], off offset:512
	global_load_dwordx4 v[224:227], v[116:117], off offset:576
	s_waitcnt vmcnt(3)
	v_pk_add_f32 v[110:111], v[110:111], v[214:215]
	v_pk_add_f32 v[108:109], v[108:109], v[212:213]
	global_store_dwordx4 v[118:119], v[108:111], off
	s_waitcnt vmcnt(3)
	v_pk_add_f32 v[106:107], v[106:107], v[218:219]
	v_pk_add_f32 v[104:105], v[104:105], v[216:217]
	global_store_dwordx4 v[118:119], v[104:107], off offset:64
	s_waitcnt vmcnt(3)
	v_pk_add_f32 v[102:103], v[102:103], v[222:223]
	v_pk_add_f32 v[100:101], v[100:101], v[220:221]
	global_store_dwordx4 v[118:119], v[100:103], off offset:512
	s_waitcnt vmcnt(3)
	v_pk_add_f32 v[98:99], v[98:99], v[226:227]
	v_pk_add_f32 v[96:97], v[96:97], v[224:225]
	global_store_dwordx4 v[118:119], v[96:99], off offset:576

;     __device__ __forceinline__ void operator()(const f32x4 (&acc)[2][2][4][2], const Unit& u, int wr, int wc, int fr, int fq) const {
;     ...
;             for (int m = 0; m < 4; ++m) { const int row = row0 + ai * HALF + m * 16;
;                 if (row < M) { float* hp = hrow(*p, row) + col0; const float* sp = FIRST ? xrow(*p, row) + col0 : hp;
; #pragma unroll
;                     for (int bj = 0; bj < 2; ++bj)
; #pragma unroll
;                         for (int n = 0; n < 2; ++n) { f32x4 h = *(const f32x4*)(sp + bj * HALF + n * 16); h += acc[ai][bj][m][n]; *(f32x4*)(hp + bj * HALF + n * 16) = h; } } }
.LBB0_894:
	s_andn2_saveexec_b64 s[18:19], s[18:19]
	v_ashrrev_i32_e32 v97, 31, v96
	s_or_b64 exec, exec, s[18:19]
	v_lshlrev_b64 v[98:99], 12, v[98:99]
	v_lshlrev_b64 v[96:97], 12, v[96:97]
	v_lshl_add_u64 v[98:99], v[100:101], 0, v[98:99]
	v_lshlrev_b64 v[100:101], 2, v[148:149]
	v_lshl_add_u64 v[96:97], v[104:105], 0, v[96:97]
	v_lshl_add_u64 v[102:103], v[98:99], 0, v[100:101]
	v_lshl_add_u64 v[100:101], v[96:97], 0, v[100:101]
	global_load_dwordx4 v[212:215], v[100:101], off
	global_load_dwordx4 v[216:219], v[100:101], off offset:64
	global_load_dwordx4 v[220:223], v[100:101], off offset:512
	global_load_dwordx4 v[224:227], v[100:101], off offset:576
	s_waitcnt vmcnt(3)
	v_pk_add_f32 v[94:95], v[94:95], v[214:215]
	v_pk_add_f32 v[92:93], v[92:93], v[212:213]
	global_store_dwordx4 v[102:103], v[92:95], off
	s_waitcnt vmcnt(3)
	v_pk_add_f32 v[90:91], v[90:91], v[218:219]
	v_pk_add_f32 v[88:89], v[88:89], v[216:217]
	global_store_dwordx4 v[102:103], v[88:91], off offset:64
	s_waitcnt vmcnt(3)
	v_pk_add_f32 v[86:87], v[86:87], v[222:223]
	v_pk_add_f32 v[84:85], v[84:85], v[220:221]
	global_store_dwordx4 v[102:103], v[84:87], off offset:512
	s_waitcnt vmcnt(3)
	v_pk_add_f32 v[82:83], v[82:83], v[226:227]
	v_pk_add_f32 v[80:81], v[80:81], v[224:225]
	global_store_dwordx4 v[102:103], v[80:83], off offset:576

;     __device__ __forceinline__ void operator()(const f32x4 (&acc)[2][2][4][2], const Unit& u, int wr, int wc, int fr, int fq) const {
;     ...
;             for (int m = 0; m < 4; ++m) { const int row = row0 + ai * HALF + m * 16;
;                 if (row < M) { float* hp = hrow(*p, row) + col0; const float* sp = FIRST ? xrow(*p, row) + col0 : hp;
; #pragma unroll
;                     for (int bj = 0; bj < 2; ++bj)
; #pragma unroll
;                         for (int n = 0; n < 2; ++n) { f32x4 h = *(const f32x4*)(sp + bj * HALF + n * 16); h += acc[ai][bj][m][n]; *(f32x4*)(hp + bj * HALF + n * 16) = h; } } }
.LBB0_904:
	s_andn2_saveexec_b64 s[18:19], s[18:19]
	v_ashrrev_i32_e32 v81, 31, v80
	s_or_b64 exec, exec, s[18:19]
	v_lshlrev_b64 v[82:83], 12, v[82:83]
	v_lshlrev_b64 v[80:81], 12, v[80:81]
	v_lshl_add_u64 v[82:83], v[84:85], 0, v[82:83]
	v_lshlrev_b64 v[84:85], 2, v[148:149]
	v_lshl_add_u64 v[80:81], v[88:89], 0, v[80:81]
	v_lshl_add_u64 v[86:87], v[82:83], 0, v[84:85]
	v_lshl_add_u64 v[84:85], v[80:81], 0, v[84:85]
	global_load_dwordx4 v[212:215], v[84:85], off
	global_load_dwordx4 v[216:219], v[84:85], off offset:64
	global_load_dwordx4 v[220:223], v[84:85], off offset:512
	global_load_dwordx4 v[224:227], v[84:85], off offset:576
	s_waitcnt vmcnt(3)
	v_pk_add_f32 v[78:79], v[78:79], v[214:215]
	v_pk_add_f32 v[76:77], v[76:77], v[212:213]
	global_store_dwordx4 v[86:87], v[76:79], off
	s_waitcnt vmcnt(3)
	v_pk_add_f32 v[74:75], v[74:75], v[218:219]
	v_pk_add_f32 v[72:73], v[72:73], v[216:217]
	global_store_dwordx4 v[86:87], v[72:75], off offset:64
	s_waitcnt vmcnt(3)
	v_pk_add_f32 v[70:71], v[70:71], v[222:223]
	v_pk_add_f32 v[68:69], v[68:69], v[220:221]
	global_store_dwordx4 v[86:87], v[68:71], off offset:512
	s_waitcnt vmcnt(3)
	v_pk_add_f32 v[66:67], v[66:67], v[226:227]
	v_pk_add_f32 v[64:65], v[64:65], v[224:225]
	global_store_dwordx4 v[86:87], v[64:67], off offset:576

;     __device__ __forceinline__ void operator()(const f32x4 (&acc)[2][2][4][2], const Unit& u, int wr, int wc, int fr, int fq) const {
;     ...
;             for (int m = 0; m < 4; ++m) { const int row = row0 + ai * HALF + m * 16;
;                 if (row < M) { float* hp = hrow(*p, row) + col0; const float* sp = FIRST ? xrow(*p, row) + col0 : hp;
; #pragma unroll
;                     for (int bj = 0; bj < 2; ++bj)
; #pragma unroll
;                         for (int n = 0; n < 2; ++n) { f32x4 h = *(const f32x4*)(sp + bj * HALF + n * 16); h += acc[ai][bj][m][n]; *(f32x4*)(hp + bj * HALF + n * 16) = h; } } }
.LBB0_914:
	s_andn2_saveexec_b64 s[18:19], s[18:19]
	v_ashrrev_i32_e32 v65, 31, v64
	s_or_b64 exec, exec, s[18:19]
	v_lshlrev_b64 v[66:67], 12, v[66:67]
	v_lshlrev_b64 v[64:65], 12, v[64:65]
	v_lshl_add_u64 v[66:67], v[68:69], 0, v[66:67]
	v_lshlrev_b64 v[68:69], 2, v[148:149]
	v_lshl_add_u64 v[64:65], v[72:73], 0, v[64:65]
	v_lshl_add_u64 v[70:71], v[66:67], 0, v[68:69]
	v_lshl_add_u64 v[68:69], v[64:65], 0, v[68:69]
	global_load_dwordx4 v[212:215], v[68:69], off
	global_load_dwordx4 v[216:219], v[68:69], off offset:64
	global_load_dwordx4 v[220:223], v[68:69], off offset:512
	global_load_dwordx4 v[224:227], v[68:69], off offset:576
	s_waitcnt vmcnt(3)
	v_pk_add_f32 v[62:63], v[62:63], v[214:215]
	v_pk_add_f32 v[60:61], v[60:61], v[212:213]
	global_store_dwordx4 v[70:71], v[60:63], off
	s_waitcnt vmcnt(3)
	v_pk_add_f32 v[58:59], v[58:59], v[218:219]
	v_pk_add_f32 v[56:57], v[56:57], v[216:217]
	global_store_dwordx4 v[70:71], v[56:59], off offset:64
	s_waitcnt vmcnt(3)
	v_pk_add_f32 v[54:55], v[54:55], v[222:223]
	v_pk_add_f32 v[52:53], v[52:53], v[220:221]
	global_store_dwordx4 v[70:71], v[52:55], off offset:512
	s_waitcnt vmcnt(3)
	v_pk_add_f32 v[50:51], v[50:51], v[226:227]
	v_pk_add_f32 v[48:49], v[48:49], v[224:225]
	global_store_dwordx4 v[70:71], v[48:51], off offset:576

;     __device__ __forceinline__ void operator()(const f32x4 (&acc)[2][2][4][2], const Unit& u, int wr, int wc, int fr, int fq) const {
;     ...
;             for (int m = 0; m < 4; ++m) { const int row = row0 + ai * HALF + m * 16;
;                 if (row < M) { float* hp = hrow(*p, row) + col0; const float* sp = FIRST ? xrow(*p, row) + col0 : hp;
; #pragma unroll
;                     for (int bj = 0; bj < 2; ++bj)
; #pragma unroll
;                         for (int n = 0; n < 2; ++n) { f32x4 h = *(const f32x4*)(sp + bj * HALF + n * 16); h += acc[ai][bj][m][n]; *(f32x4*)(hp + bj * HALF + n * 16) = h; } } }
.LBB0_924:
	s_andn2_saveexec_b64 s[18:19], s[18:19]
	v_ashrrev_i32_e32 v49, 31, v48
	s_or_b64 exec, exec, s[18:19]
	v_lshlrev_b64 v[50:51], 12, v[50:51]
	v_lshlrev_b64 v[48:49], 12, v[48:49]
	v_lshl_add_u64 v[50:51], v[52:53], 0, v[50:51]
	v_lshlrev_b64 v[52:53], 2, v[148:149]
	v_lshl_add_u64 v[48:49], v[56:57], 0, v[48:49]
	v_lshl_add_u64 v[54:55], v[50:51], 0, v[52:53]
	v_lshl_add_u64 v[52:53], v[48:49], 0, v[52:53]
	global_load_dwordx4 v[212:215], v[52:53], off
	global_load_dwordx4 v[216:219], v[52:53], off offset:64
	global_load_dwordx4 v[220:223], v[52:53], off offset:512
	global_load_dwordx4 v[224:227], v[52:53], off offset:576
	s_waitcnt vmcnt(3)
	v_pk_add_f32 v[46:47], v[46:47], v[214:215]
	v_pk_add_f32 v[44:45], v[44:45], v[212:213]
	global_store_dwordx4 v[54:55], v[44:47], off
	s_waitcnt vmcnt(3)
	v_pk_add_f32 v[42:43], v[42:43], v[218:219]
	v_pk_add_f32 v[40:41], v[40:41], v[216:217]
	global_store_dwordx4 v[54:55], v[40:43], off offset:64
	s_waitcnt vmcnt(3)
	v_pk_add_f32 v[38:39], v[38:39], v[222:223]
	v_pk_add_f32 v[36:37], v[36:37], v[220:221]
	global_store_dwordx4 v[54:55], v[36:39], off offset:512
	s_waitcnt vmcnt(3)
	v_pk_add_f32 v[34:35], v[34:35], v[226:227]
	v_pk_add_f32 v[32:33], v[32:33], v[224:225]
	global_store_dwordx4 v[54:55], v[32:35], off offset:576

;     __device__ __forceinline__ void operator()(const f32x4 (&acc)[2][2][4][2], const Unit& u, int wr, int wc, int fr, int fq) const {
;     ...
;             for (int m = 0; m < 4; ++m) { const int row = row0 + ai * HALF + m * 16;
;                 if (row < M) { float* hp = hrow(*p, row) + col0; const float* sp = FIRST ? xrow(*p, row) + col0 : hp;
; #pragma unroll
;                     for (int bj = 0; bj < 2; ++bj)
; #pragma unroll
;                         for (int n = 0; n < 2; ++n) { f32x4 h = *(const f32x4*)(sp + bj * HALF + n * 16); h += acc[ai][bj][m][n]; *(f32x4*)(hp + bj * HALF + n * 16) = h; } } }
.LBB0_934:
	s_andn2_saveexec_b64 s[18:19], s[18:19]
	v_ashrrev_i32_e32 v33, 31, v32
	s_or_b64 exec, exec, s[18:19]
	v_lshlrev_b64 v[34:35], 12, v[34:35]
	v_lshlrev_b64 v[32:33], 12, v[32:33]
	v_lshl_add_u64 v[34:35], v[36:37], 0, v[34:35]
	v_lshlrev_b64 v[36:37], 2, v[148:149]
	v_lshl_add_u64 v[32:33], v[40:41], 0, v[32:33]
	v_lshl_add_u64 v[38:39], v[34:35], 0, v[36:37]
	v_lshl_add_u64 v[36:37], v[32:33], 0, v[36:37]
	global_load_dwordx4 v[212:215], v[36:37], off
	global_load_dwordx4 v[216:219], v[36:37], off offset:64
	global_load_dwordx4 v[220:223], v[36:37], off offset:512
	global_load_dwordx4 v[224:227], v[36:37], off offset:576
	s_waitcnt vmcnt(3)
	v_pk_add_f32 v[30:31], v[30:31], v[214:215]
	v_pk_add_f32 v[28:29], v[28:29], v[212:213]
	global_store_dwordx4 v[38:39], v[28:31], off
	s_waitcnt vmcnt(3)
	v_pk_add_f32 v[26:27], v[26:27], v[218:219]
	v_pk_add_f32 v[24:25], v[24:25], v[216:217]
	global_store_dwordx4 v[38:39], v[24:27], off offset:64
	s_waitcnt vmcnt(3)
	v_pk_add_f32 v[22:23], v[22:23], v[222:223]
	v_pk_add_f32 v[20:21], v[20:21], v[220:221]
	global_store_dwordx4 v[38:39], v[20:23], off offset:512
	s_waitcnt vmcnt(3)
	v_pk_add_f32 v[18:19], v[18:19], v[226:227]
	v_pk_add_f32 v[16:17], v[16:17], v[224:225]
	global_store_dwordx4 v[38:39], v[16:19], off offset:576

;     __device__ __forceinline__ void operator()(const f32x4 (&acc)[2][2][4][2], const Unit& u, int wr, int wc, int fr, int fq) const {
;     ...
;             for (int m = 0; m < 4; ++m) { const int row = row0 + ai * HALF + m * 16;
;                 if (row < M) { float* hp = hrow(*p, row) + col0; const float* sp = FIRST ? xrow(*p, row) + col0 : hp;
; #pragma unroll
;                     for (int bj = 0; bj < 2; ++bj)
; #pragma unroll
;                         for (int n = 0; n < 2; ++n) { f32x4 h = *(const f32x4*)(sp + bj * HALF + n * 16); h += acc[ai][bj][m][n]; *(f32x4*)(hp + bj * HALF + n * 16) = h; } } }
.LBB0_944:
	s_andn2_saveexec_b64 s[18:19], s[18:19]
	v_ashrrev_i32_e32 v17, 31, v16
	s_or_b64 exec, exec, s[18:19]
	v_lshlrev_b64 v[18:19], 12, v[18:19]
	v_lshlrev_b64 v[16:17], 12, v[16:17]
	v_lshl_add_u64 v[18:19], v[20:21], 0, v[18:19]
	v_lshlrev_b64 v[20:21], 2, v[148:149]
	v_lshl_add_u64 v[16:17], v[24:25], 0, v[16:17]
	v_lshl_add_u64 v[22:23], v[18:19], 0, v[20:21]
	v_lshl_add_u64 v[20:21], v[16:17], 0, v[20:21]
	global_load_dwordx4 v[212:215], v[20:21], off
	global_load_dwordx4 v[216:219], v[20:21], off offset:64
	global_load_dwordx4 v[220:223], v[20:21], off offset:512
	global_load_dwordx4 v[224:227], v[20:21], off offset:576
	s_waitcnt vmcnt(3)
	v_pk_add_f32 v[14:15], v[14:15], v[214:215]
	v_pk_add_f32 v[12:13], v[12:13], v[212:213]
	global_store_dwordx4 v[22:23], v[12:15], off
	s_waitcnt vmcnt(3)
	v_pk_add_f32 v[10:11], v[10:11], v[218:219]
	v_pk_add_f32 v[8:9], v[8:9], v[216:217]
	global_store_dwordx4 v[22:23], v[8:11], off offset:64
	s_waitcnt vmcnt(3)
	v_pk_add_f32 v[6:7], v[6:7], v[222:223]
	v_pk_add_f32 v[4:5], v[4:5], v[220:221]
	global_store_dwordx4 v[22:23], v[4:7], off offset:512
	s_waitcnt vmcnt(3)
	v_pk_add_f32 v[2:3], v[2:3], v[226:227]
	v_pk_add_f32 v[0:1], v[0:1], v[224:225]
	global_store_dwordx4 v[22:23], v[0:3], off offset:576

; #define PG8_LAS __attribute__((address_space(3)))
; DEVI int obid() { int t = blockIdx.x; asm volatile("" : "+s"(t)); return t; }
;     __device__ __forceinline__ bool next(int i, Unit& u) const { if (i != 0 || c >= n) return false; u.pm = pm; u.pn = c & 3; return true; }
;     __host__ __device__ bool next(int i, Unit& u) const {
;         const long L = (long)i * G + c; if (L >= nwg) return false;
;         int wgid = (int)L; { const int q = nwg / NXCD, r = nwg % NXCD, xcd = wgid % NXCD, off = wgid / NXCD; wgid = (xcd < r ? xcd * (q + 1) : r * (q + 1) + (xcd - r) * q) + off; }
;         const int nig = WGM * nN, gid = wgid / nig, fm = gid * WGM, gsz = (nM - fm) < WGM ? (nM - fm) : WGM;
;         u.pm = fm + ((wgid % nig) % gsz); u.pn = (wgid % nig) / gsz; return true;
; template <class Epi>
; __device__ __forceinline__ void run_gemm(unsigned char* smem, const bf16_t* A, int lda, const bf16_t* Bt, int N, int K, const Epi& E) {
;   pg8::Gemm g{A, Bt, MP, N, K, lda, K};
;   pg8::StaticOrder S; S.init(MP, N, (int)gridDim.x, obid());
;   pg8::gemm_phase<Epi, pg8::StaticOrder, true, true>((PG8_LAS unsigned char*)smem, g, S, E);
.LBB0_1453:
	v_readlane_b32 s35, v254, 22
	s_sub_i32 s35, 0xff, s35
	v_mov_b32_e32 v0, v128
	s_cmpk_lt_i32 s35, 0x204
	v_readlane_b32 s72, v255, 8
	s_cselect_b64 s[0:1], -1, 0
	s_cmpk_gt_i32 s35, 0x203
	v_readfirstlane_b32 s8, v0
	v_readlane_b32 s73, v255, 9
	s_cbranch_scc1 .LBB0_1459
	s_ashr_i32 s2, s35, 31
	s_lshr_b32 s2, s2, 29
	s_add_i32 s4, s35, s2
	s_and_b32 s2, s4, -8
	s_sub_i32 s5, s35, s2
	s_cmp_gt_i32 s5, 3
	s_mov_b64 s[2:3], -1
	s_cbranch_scc0 .LBB0_1456
	s_lshl_b32 s2, s5, 6
	s_or_b32 s6, s2, 4
	s_mov_b64 s[2:3], 0

; DEVI int obid() { int t = blockIdx.x; asm volatile("" : "+s"(t)); return t; }
; __global__ void __launch_bounds__(NT, 2) fwd_megakernel(Params p) {
;     ...
;       for (int it = obid(); it < 64; it += gridDim.x) fcum_item(p, smem, it);
.LBB0_1577:
	v_readlane_b32 s8, v254, 22
	s_sub_i32 s8, s8, 0x83
	s_cmp_gt_u32 s8, 63
	s_cbranch_scc0 .LBB0_1582

;     __device__ __forceinline__ void operator()(const f32x4 (&acc)[2][2][4][2], const Unit& u, int wr, int wc, int fr, int fq) const {
;     ...
;             for (int m = 0; m < 4; ++m) { const int row = row0 + ai * HALF + m * 16;
;                 if (row < M) { float* hp = hrow(*p, row) + col0; const float* sp = FIRST ? xrow(*p, row) + col0 : hp;
; #pragma unroll
;                     for (int bj = 0; bj < 2; ++bj)
; #pragma unroll
;                         for (int n = 0; n < 2; ++n) { f32x4 h = *(const f32x4*)(sp + bj * HALF + n * 16); h += acc[ai][bj][m][n]; *(f32x4*)(hp + bj * HALF + n * 16) = h; } } }
.LBB0_1973:
	s_andn2_saveexec_b64 s[18:19], s[18:19]
	v_lshl_add_u32 v160, v162, 4, v170
	v_ashrrev_i32_e32 v161, 31, v160
	v_mov_b64_e32 v[164:165], s[14:15]
	s_or_b64 exec, exec, s[18:19]
	v_lshlrev_b64 v[160:161], 12, v[160:161]
	v_lshl_add_u64 v[160:161], v[164:165], 0, v[160:161]
	v_lshl_add_u64 v[164:165], v[158:159], 2, v[160:161]
	global_load_dwordx4 v[212:215], v[164:165], off
	global_load_dwordx4 v[216:219], v[164:165], off offset:64
	global_load_dwordx4 v[220:223], v[164:165], off offset:512
	global_load_dwordx4 v[224:227], v[164:165], off offset:576
	s_waitcnt vmcnt(3)
	v_pk_add_f32 v[126:127], v[126:127], v[214:215]
	v_pk_add_f32 v[124:125], v[124:125], v[212:213]
	global_store_dwordx4 v[164:165], v[124:127], off
	s_waitcnt vmcnt(3)
	v_pk_add_f32 v[122:123], v[122:123], v[218:219]
	v_pk_add_f32 v[120:121], v[120:121], v[216:217]
	global_store_dwordx4 v[164:165], v[120:123], off offset:64
	s_waitcnt vmcnt(3)
	v_pk_add_f32 v[118:119], v[118:119], v[222:223]
	v_pk_add_f32 v[116:117], v[116:117], v[220:221]
	global_store_dwordx4 v[164:165], v[116:119], off offset:512
	s_waitcnt vmcnt(3)
	v_pk_add_f32 v[114:115], v[114:115], v[226:227]
	v_pk_add_f32 v[112:113], v[112:113], v[224:225]
	global_store_dwordx4 v[164:165], v[112:115], off offset:576

;     __device__ __forceinline__ void operator()(const f32x4 (&acc)[2][2][4][2], const Unit& u, int wr, int wc, int fr, int fq) const {
;     ...
;             for (int m = 0; m < 4; ++m) { const int row = row0 + ai * HALF + m * 16;
;                 if (row < M) { float* hp = hrow(*p, row) + col0; const float* sp = FIRST ? xrow(*p, row) + col0 : hp;
; #pragma unroll
;                     for (int bj = 0; bj < 2; ++bj)
; #pragma unroll
;                         for (int n = 0; n < 2; ++n) { f32x4 h = *(const f32x4*)(sp + bj * HALF + n * 16); h += acc[ai][bj][m][n]; *(f32x4*)(hp + bj * HALF + n * 16) = h; } } }
.LBB0_1979:
	s_andn2_saveexec_b64 s[18:19], s[18:19]
	v_lshl_add_u32 v112, v114, 4, v118
	v_ashrrev_i32_e32 v113, 31, v112
	v_mov_b64_e32 v[116:117], s[14:15]
	s_or_b64 exec, exec, s[18:19]
	v_lshlrev_b64 v[112:113], 12, v[112:113]
	v_lshl_add_u64 v[112:113], v[116:117], 0, v[112:113]
	v_lshl_add_u64 v[116:117], v[158:159], 2, v[112:113]
	global_load_dwordx4 v[212:215], v[116:117], off
	global_load_dwordx4 v[216:219], v[116:117], off offset:64
	global_load_dwordx4 v[220:223], v[116:117], off offset:512
	global_load_dwordx4 v[224:227], v[116:117], off offset:576
	s_waitcnt vmcnt(3)
	v_pk_add_f32 v[110:111], v[110:111], v[214:215]
	v_pk_add_f32 v[108:109], v[108:109], v[212:213]
	global_store_dwordx4 v[116:117], v[108:111], off
	s_waitcnt vmcnt(3)
	v_pk_add_f32 v[106:107], v[106:107], v[218:219]
	v_pk_add_f32 v[104:105], v[104:105], v[216:217]
	global_store_dwordx4 v[116:117], v[104:107], off offset:64
	s_waitcnt vmcnt(3)
	v_pk_add_f32 v[102:103], v[102:103], v[222:223]
	v_pk_add_f32 v[100:101], v[100:101], v[220:221]
	global_store_dwordx4 v[116:117], v[100:103], off offset:512
	s_waitcnt vmcnt(3)
	v_pk_add_f32 v[98:99], v[98:99], v[226:227]
	v_pk_add_f32 v[96:97], v[96:97], v[224:225]
	global_store_dwordx4 v[116:117], v[96:99], off offset:576

;     __device__ __forceinline__ void operator()(const f32x4 (&acc)[2][2][4][2], const Unit& u, int wr, int wc, int fr, int fq) const {
;     ...
;             for (int m = 0; m < 4; ++m) { const int row = row0 + ai * HALF + m * 16;
;                 if (row < M) { float* hp = hrow(*p, row) + col0; const float* sp = FIRST ? xrow(*p, row) + col0 : hp;
; #pragma unroll
;                     for (int bj = 0; bj < 2; ++bj)
; #pragma unroll
;                         for (int n = 0; n < 2; ++n) { f32x4 h = *(const f32x4*)(sp + bj * HALF + n * 16); h += acc[ai][bj][m][n]; *(f32x4*)(hp + bj * HALF + n * 16) = h; } } }
.LBB0_1985:
	s_andn2_saveexec_b64 s[18:19], s[18:19]
	v_lshl_add_u32 v96, v98, 4, v102
	v_ashrrev_i32_e32 v97, 31, v96
	v_mov_b64_e32 v[100:101], s[14:15]
	s_or_b64 exec, exec, s[18:19]
	v_lshlrev_b64 v[96:97], 12, v[96:97]
	v_lshl_add_u64 v[96:97], v[100:101], 0, v[96:97]
	v_lshl_add_u64 v[100:101], v[158:159], 2, v[96:97]
	global_load_dwordx4 v[212:215], v[100:101], off
	global_load_dwordx4 v[216:219], v[100:101], off offset:64
	global_load_dwordx4 v[220:223], v[100:101], off offset:512
	global_load_dwordx4 v[224:227], v[100:101], off offset:576
	s_waitcnt vmcnt(3)
	v_pk_add_f32 v[94:95], v[94:95], v[214:215]
	v_pk_add_f32 v[92:93], v[92:93], v[212:213]
	global_store_dwordx4 v[100:101], v[92:95], off
	s_waitcnt vmcnt(3)
	v_pk_add_f32 v[90:91], v[90:91], v[218:219]
	v_pk_add_f32 v[88:89], v[88:89], v[216:217]
	global_store_dwordx4 v[100:101], v[88:91], off offset:64
	s_waitcnt vmcnt(3)
	v_pk_add_f32 v[86:87], v[86:87], v[222:223]
	v_pk_add_f32 v[84:85], v[84:85], v[220:221]
	global_store_dwordx4 v[100:101], v[84:87], off offset:512
	s_waitcnt vmcnt(3)
	v_pk_add_f32 v[82:83], v[82:83], v[226:227]
	v_pk_add_f32 v[80:81], v[80:81], v[224:225]
	global_store_dwordx4 v[100:101], v[80:83], off offset:576

;     __device__ __forceinline__ void operator()(const f32x4 (&acc)[2][2][4][2], const Unit& u, int wr, int wc, int fr, int fq) const {
;     ...
;             for (int m = 0; m < 4; ++m) { const int row = row0 + ai * HALF + m * 16;
;                 if (row < M) { float* hp = hrow(*p, row) + col0; const float* sp = FIRST ? xrow(*p, row) + col0 : hp;
; #pragma unroll
;                     for (int bj = 0; bj < 2; ++bj)
; #pragma unroll
;                         for (int n = 0; n < 2; ++n) { f32x4 h = *(const f32x4*)(sp + bj * HALF + n * 16); h += acc[ai][bj][m][n]; *(f32x4*)(hp + bj * HALF + n * 16) = h; } } }
.LBB0_1991:
	s_andn2_saveexec_b64 s[18:19], s[18:19]
	v_lshl_add_u32 v80, v82, 4, v86
	v_ashrrev_i32_e32 v81, 31, v80
	v_mov_b64_e32 v[84:85], s[14:15]
	s_or_b64 exec, exec, s[18:19]
	v_lshlrev_b64 v[80:81], 12, v[80:81]
	v_lshl_add_u64 v[80:81], v[84:85], 0, v[80:81]
	v_lshl_add_u64 v[84:85], v[158:159], 2, v[80:81]
	global_load_dwordx4 v[212:215], v[84:85], off
	global_load_dwordx4 v[216:219], v[84:85], off offset:64
	global_load_dwordx4 v[220:223], v[84:85], off offset:512
	global_load_dwordx4 v[224:227], v[84:85], off offset:576
	s_waitcnt vmcnt(3)
	v_pk_add_f32 v[78:79], v[78:79], v[214:215]
	v_pk_add_f32 v[76:77], v[76:77], v[212:213]
	global_store_dwordx4 v[84:85], v[76:79], off
	s_waitcnt vmcnt(3)
	v_pk_add_f32 v[74:75], v[74:75], v[218:219]
	v_pk_add_f32 v[72:73], v[72:73], v[216:217]
	global_store_dwordx4 v[84:85], v[72:75], off offset:64
	s_waitcnt vmcnt(3)
	v_pk_add_f32 v[70:71], v[70:71], v[222:223]
	v_pk_add_f32 v[68:69], v[68:69], v[220:221]
	global_store_dwordx4 v[84:85], v[68:71], off offset:512
	s_waitcnt vmcnt(3)
	v_pk_add_f32 v[66:67], v[66:67], v[226:227]
	v_pk_add_f32 v[64:65], v[64:65], v[224:225]
	global_store_dwordx4 v[84:85], v[64:67], off offset:576

;     __device__ __forceinline__ void operator()(const f32x4 (&acc)[2][2][4][2], const Unit& u, int wr, int wc, int fr, int fq) const {
;     ...
;             for (int m = 0; m < 4; ++m) { const int row = row0 + ai * HALF + m * 16;
;                 if (row < M) { float* hp = hrow(*p, row) + col0; const float* sp = FIRST ? xrow(*p, row) + col0 : hp;
; #pragma unroll
;                     for (int bj = 0; bj < 2; ++bj)
; #pragma unroll
;                         for (int n = 0; n < 2; ++n) { f32x4 h = *(const f32x4*)(sp + bj * HALF + n * 16); h += acc[ai][bj][m][n]; *(f32x4*)(hp + bj * HALF + n * 16) = h; } } }
.LBB0_1997:
	s_andn2_saveexec_b64 s[18:19], s[18:19]
	v_lshl_add_u32 v64, v66, 4, v70
	v_ashrrev_i32_e32 v65, 31, v64
	v_mov_b64_e32 v[68:69], s[14:15]
	s_or_b64 exec, exec, s[18:19]
	v_lshlrev_b64 v[64:65], 12, v[64:65]
	v_lshl_add_u64 v[64:65], v[68:69], 0, v[64:65]
	v_lshl_add_u64 v[68:69], v[158:159], 2, v[64:65]
	global_load_dwordx4 v[212:215], v[68:69], off
	global_load_dwordx4 v[216:219], v[68:69], off offset:64
	global_load_dwordx4 v[220:223], v[68:69], off offset:512
	global_load_dwordx4 v[224:227], v[68:69], off offset:576
	s_waitcnt vmcnt(3)
	v_pk_add_f32 v[62:63], v[62:63], v[214:215]
	v_pk_add_f32 v[60:61], v[60:61], v[212:213]
	global_store_dwordx4 v[68:69], v[60:63], off
	s_waitcnt vmcnt(3)
	v_pk_add_f32 v[58:59], v[58:59], v[218:219]
	v_pk_add_f32 v[56:57], v[56:57], v[216:217]
	global_store_dwordx4 v[68:69], v[56:59], off offset:64
	s_waitcnt vmcnt(3)
	v_pk_add_f32 v[54:55], v[54:55], v[222:223]
	v_pk_add_f32 v[52:53], v[52:53], v[220:221]
	global_store_dwordx4 v[68:69], v[52:55], off offset:512
	s_waitcnt vmcnt(3)
	v_pk_add_f32 v[50:51], v[50:51], v[226:227]
	v_pk_add_f32 v[48:49], v[48:49], v[224:225]
	global_store_dwordx4 v[68:69], v[48:51], off offset:576

;     __device__ __forceinline__ void operator()(const f32x4 (&acc)[2][2][4][2], const Unit& u, int wr, int wc, int fr, int fq) const {
;     ...
;             for (int m = 0; m < 4; ++m) { const int row = row0 + ai * HALF + m * 16;
;                 if (row < M) { float* hp = hrow(*p, row) + col0; const float* sp = FIRST ? xrow(*p, row) + col0 : hp;
; #pragma unroll
;                     for (int bj = 0; bj < 2; ++bj)
; #pragma unroll
;                         for (int n = 0; n < 2; ++n) { f32x4 h = *(const f32x4*)(sp + bj * HALF + n * 16); h += acc[ai][bj][m][n]; *(f32x4*)(hp + bj * HALF + n * 16) = h; } } }
.LBB0_2003:
	s_andn2_saveexec_b64 s[18:19], s[18:19]
	v_lshl_add_u32 v48, v50, 4, v54
	v_ashrrev_i32_e32 v49, 31, v48
	v_mov_b64_e32 v[52:53], s[14:15]
	s_or_b64 exec, exec, s[18:19]
	v_lshlrev_b64 v[48:49], 12, v[48:49]
	v_lshl_add_u64 v[48:49], v[52:53], 0, v[48:49]
	v_lshl_add_u64 v[52:53], v[158:159], 2, v[48:49]
	global_load_dwordx4 v[212:215], v[52:53], off
	global_load_dwordx4 v[216:219], v[52:53], off offset:64
	global_load_dwordx4 v[220:223], v[52:53], off offset:512
	global_load_dwordx4 v[224:227], v[52:53], off offset:576
	s_waitcnt vmcnt(3)
	v_pk_add_f32 v[46:47], v[46:47], v[214:215]
	v_pk_add_f32 v[44:45], v[44:45], v[212:213]
	global_store_dwordx4 v[52:53], v[44:47], off
	s_waitcnt vmcnt(3)
	v_pk_add_f32 v[42:43], v[42:43], v[218:219]
	v_pk_add_f32 v[40:41], v[40:41], v[216:217]
	global_store_dwordx4 v[52:53], v[40:43], off offset:64
	s_waitcnt vmcnt(3)
	v_pk_add_f32 v[38:39], v[38:39], v[222:223]
	v_pk_add_f32 v[36:37], v[36:37], v[220:221]
	global_store_dwordx4 v[52:53], v[36:39], off offset:512
	s_waitcnt vmcnt(3)
	v_pk_add_f32 v[34:35], v[34:35], v[226:227]
	v_pk_add_f32 v[32:33], v[32:33], v[224:225]
	global_store_dwordx4 v[52:53], v[32:35], off offset:576

;     __device__ __forceinline__ void operator()(const f32x4 (&acc)[2][2][4][2], const Unit& u, int wr, int wc, int fr, int fq) const {
;     ...
;             for (int m = 0; m < 4; ++m) { const int row = row0 + ai * HALF + m * 16;
;                 if (row < M) { float* hp = hrow(*p, row) + col0; const float* sp = FIRST ? xrow(*p, row) + col0 : hp;
; #pragma unroll
;                     for (int bj = 0; bj < 2; ++bj)
; #pragma unroll
;                         for (int n = 0; n < 2; ++n) { f32x4 h = *(const f32x4*)(sp + bj * HALF + n * 16); h += acc[ai][bj][m][n]; *(f32x4*)(hp + bj * HALF + n * 16) = h; } } }
.LBB0_2009:
	s_andn2_saveexec_b64 s[18:19], s[18:19]
	v_lshl_add_u32 v32, v34, 4, v38
	v_ashrrev_i32_e32 v33, 31, v32
	v_mov_b64_e32 v[36:37], s[14:15]
	s_or_b64 exec, exec, s[18:19]
	v_lshlrev_b64 v[32:33], 12, v[32:33]
	v_lshl_add_u64 v[32:33], v[36:37], 0, v[32:33]
	v_lshl_add_u64 v[36:37], v[158:159], 2, v[32:33]
	global_load_dwordx4 v[212:215], v[36:37], off
	global_load_dwordx4 v[216:219], v[36:37], off offset:64
	global_load_dwordx4 v[220:223], v[36:37], off offset:512
	global_load_dwordx4 v[224:227], v[36:37], off offset:576
	s_waitcnt vmcnt(3)
	v_pk_add_f32 v[30:31], v[30:31], v[214:215]
	v_pk_add_f32 v[28:29], v[28:29], v[212:213]
	global_store_dwordx4 v[36:37], v[28:31], off
	s_waitcnt vmcnt(3)
	v_pk_add_f32 v[26:27], v[26:27], v[218:219]
	v_pk_add_f32 v[24:25], v[24:25], v[216:217]
	global_store_dwordx4 v[36:37], v[24:27], off offset:64
	s_waitcnt vmcnt(3)
	v_pk_add_f32 v[22:23], v[22:23], v[222:223]
	v_pk_add_f32 v[20:21], v[20:21], v[220:221]
	global_store_dwordx4 v[36:37], v[20:23], off offset:512
	s_waitcnt vmcnt(3)
	v_pk_add_f32 v[18:19], v[18:19], v[226:227]
	v_pk_add_f32 v[16:17], v[16:17], v[224:225]
	global_store_dwordx4 v[36:37], v[16:19], off offset:576

;     __device__ __forceinline__ void operator()(const f32x4 (&acc)[2][2][4][2], const Unit& u, int wr, int wc, int fr, int fq) const {
;     ...
;             for (int m = 0; m < 4; ++m) { const int row = row0 + ai * HALF + m * 16;
;                 if (row < M) { float* hp = hrow(*p, row) + col0; const float* sp = FIRST ? xrow(*p, row) + col0 : hp;
; #pragma unroll
;                     for (int bj = 0; bj < 2; ++bj)
; #pragma unroll
;                         for (int n = 0; n < 2; ++n) { f32x4 h = *(const f32x4*)(sp + bj * HALF + n * 16); h += acc[ai][bj][m][n]; *(f32x4*)(hp + bj * HALF + n * 16) = h; } } }
.LBB0_2015:
	s_andn2_saveexec_b64 s[18:19], s[18:19]
	v_lshl_add_u32 v16, v18, 4, v22
	v_ashrrev_i32_e32 v17, 31, v16
	v_mov_b64_e32 v[20:21], s[14:15]
	s_or_b64 exec, exec, s[18:19]
	v_lshlrev_b64 v[16:17], 12, v[16:17]
	v_lshl_add_u64 v[16:17], v[20:21], 0, v[16:17]
	v_lshl_add_u64 v[20:21], v[158:159], 2, v[16:17]
	global_load_dwordx4 v[212:215], v[20:21], off
	global_load_dwordx4 v[216:219], v[20:21], off offset:64
	global_load_dwordx4 v[220:223], v[20:21], off offset:512
	global_load_dwordx4 v[224:227], v[20:21], off offset:576
	s_waitcnt vmcnt(3)
	v_pk_add_f32 v[14:15], v[14:15], v[214:215]
	v_pk_add_f32 v[12:13], v[12:13], v[212:213]
	global_store_dwordx4 v[20:21], v[12:15], off
	s_waitcnt vmcnt(3)
	v_pk_add_f32 v[10:11], v[10:11], v[218:219]
	v_pk_add_f32 v[8:9], v[8:9], v[216:217]
	global_store_dwordx4 v[20:21], v[8:11], off offset:64
	s_waitcnt vmcnt(3)
	v_pk_add_f32 v[6:7], v[6:7], v[222:223]
	v_pk_add_f32 v[4:5], v[4:5], v[220:221]
	global_store_dwordx4 v[20:21], v[4:7], off offset:512
	s_waitcnt vmcnt(3)
	v_pk_add_f32 v[2:3], v[2:3], v[226:227]
	v_pk_add_f32 v[0:1], v[0:1], v[224:225]
	global_store_dwordx4 v[20:21], v[0:3], off offset:576

;     __device__ __forceinline__ void operator()(const f32x4 (&acc)[2][2][4][2], const Unit& u, int wr, int wc, int fr, int fq) const {
;     ...
;             for (int m = 0; m < 4; ++m) { const int row = row0 + ai * HALF + m * 16;
;                 if (row < M) { float* hp = hrow(*p, row) + col0; const float* sp = FIRST ? xrow(*p, row) + col0 : hp;
; #pragma unroll
;                     for (int bj = 0; bj < 2; ++bj)
; #pragma unroll
;                         for (int n = 0; n < 2; ++n) { f32x4 h = *(const f32x4*)(sp + bj * HALF + n * 16); h += acc[ai][bj][m][n]; *(f32x4*)(hp + bj * HALF + n * 16) = h; } } }
.LBB0_2381:
	s_andn2_saveexec_b64 s[18:19], s[18:19]
	v_lshl_add_u32 v64, v66, 4, v70
	v_ashrrev_i32_e32 v65, 31, v64
	v_mov_b64_e32 v[68:69], s[14:15]
	s_or_b64 exec, exec, s[18:19]
	v_lshlrev_b64 v[64:65], 12, v[64:65]
	v_lshl_add_u64 v[64:65], v[68:69], 0, v[64:65]
	v_lshl_add_u64 v[68:69], v[158:159], 2, v[64:65]
	global_load_dwordx4 v[212:215], v[68:69], off
	global_load_dwordx4 v[216:219], v[68:69], off offset:64
	global_load_dwordx4 v[220:223], v[68:69], off offset:512
	global_load_dwordx4 v[224:227], v[68:69], off offset:576
	s_waitcnt vmcnt(3)
	v_pk_add_f32 v[62:63], v[62:63], v[214:215]
	v_pk_add_f32 v[60:61], v[60:61], v[212:213]
	global_store_dwordx4 v[68:69], v[60:63], off
	s_waitcnt vmcnt(3)
	v_pk_add_f32 v[58:59], v[58:59], v[218:219]
	v_pk_add_f32 v[56:57], v[56:57], v[216:217]
	global_store_dwordx4 v[68:69], v[56:59], off offset:64
	s_waitcnt vmcnt(3)
	v_pk_add_f32 v[54:55], v[54:55], v[222:223]
	v_pk_add_f32 v[52:53], v[52:53], v[220:221]
	global_store_dwordx4 v[68:69], v[52:55], off offset:512
	s_waitcnt vmcnt(3)
	v_pk_add_f32 v[50:51], v[50:51], v[226:227]
	v_pk_add_f32 v[48:49], v[48:49], v[224:225]
	global_store_dwordx4 v[68:69], v[48:51], off offset:576
	s_or_b64 exec, exec, s[16:17]
	v_cmp_gt_i32_e32 vcc, s75, v169
	s_and_saveexec_b64 s[16:17], vcc
	s_cbranch_execnz .LBB0_2386

;     __device__ __forceinline__ void operator()(const f32x4 (&acc)[2][2][4][2], const Unit& u, int wr, int wc, int fr, int fq) const {
;     ...
;             for (int m = 0; m < 4; ++m) { const int row = row0 + ai * HALF + m * 16;
;                 if (row < M) { float* hp = hrow(*p, row) + col0; const float* sp = FIRST ? xrow(*p, row) + col0 : hp;
; #pragma unroll
;                     for (int bj = 0; bj < 2; ++bj)
; #pragma unroll
;                         for (int n = 0; n < 2; ++n) { f32x4 h = *(const f32x4*)(sp + bj * HALF + n * 16); h += acc[ai][bj][m][n]; *(f32x4*)(hp + bj * HALF + n * 16) = h; } } }
.LBB0_2388:
	s_andn2_saveexec_b64 s[18:19], s[18:19]
	v_lshl_add_u32 v48, v50, 4, v54
	v_ashrrev_i32_e32 v49, 31, v48
	v_mov_b64_e32 v[52:53], s[14:15]
	s_or_b64 exec, exec, s[18:19]
	v_lshlrev_b64 v[48:49], 12, v[48:49]
	v_lshl_add_u64 v[48:49], v[52:53], 0, v[48:49]
	v_lshl_add_u64 v[52:53], v[158:159], 2, v[48:49]
	global_load_dwordx4 v[212:215], v[52:53], off
	global_load_dwordx4 v[216:219], v[52:53], off offset:64
	global_load_dwordx4 v[220:223], v[52:53], off offset:512
	global_load_dwordx4 v[224:227], v[52:53], off offset:576
	s_waitcnt vmcnt(3)
	v_pk_add_f32 v[46:47], v[46:47], v[214:215]
	v_pk_add_f32 v[44:45], v[44:45], v[212:213]
	global_store_dwordx4 v[52:53], v[44:47], off
	s_waitcnt vmcnt(3)
	v_pk_add_f32 v[42:43], v[42:43], v[218:219]
	v_pk_add_f32 v[40:41], v[40:41], v[216:217]
	global_store_dwordx4 v[52:53], v[40:43], off offset:64
	s_waitcnt vmcnt(3)
	v_pk_add_f32 v[38:39], v[38:39], v[222:223]
	v_pk_add_f32 v[36:37], v[36:37], v[220:221]
	global_store_dwordx4 v[52:53], v[36:39], off offset:512
	s_waitcnt vmcnt(3)
	v_pk_add_f32 v[34:35], v[34:35], v[226:227]
	v_pk_add_f32 v[32:33], v[32:33], v[224:225]
	global_store_dwordx4 v[52:53], v[32:35], off offset:576
	s_or_b64 exec, exec, s[16:17]
	v_cmp_gt_i32_e32 vcc, s83, v169
	s_and_saveexec_b64 s[16:17], vcc
	s_cbranch_execz .LBB0_2396
